# P10 unit tail de-serialised: the four 16-byte norm-weight loads issued together before the barrier into spare registers, consumed behind counted waits; stores no longer waited on
# speedup vs baseline: 1.0620x; 1.0107x over previous
.LBB0_978:
	s_or_b64 exec, exec, s[0:1]
	s_mov_b32 s61, s69
	v_lshl_add_u64 v[20:21], v[114:115], 0, s[60:61]
	global_load_dwordx4 v[198:201], v[20:21], off
	global_load_dwordx4 v[202:205], v[20:21], off offset:64
	global_load_dwordx4 v[208:211], v[20:21], off offset:128
	global_load_dwordx4 v[212:215], v[20:21], off offset:192
	s_waitcnt lgkmcnt(0)
	s_barrier
	ds_read_b64 v[22:23], v140 offset:57344
	v_add_u32_e32 v24, s74, v135
	v_ashrrev_i32_e32 v25, 31, v24
	v_lshlrev_b64 v[24:25], 11, v[24:25]
	s_waitcnt vmcnt(7)
	v_lshlrev_b32_e32 v26, 16, v126
	s_waitcnt lgkmcnt(0)
	v_add_f32_e32 v22, v22, v23
	v_fmamk_f32 v22, v22, 0x3c000000, v147
	v_mul_f32_e32 v23, 0x4b800000, v22
	v_cmp_gt_f32_e64 s[0:1], s72, v22
	v_and_b32_e32 v27, 0xffff0000, v126
	v_lshlrev_b32_e32 v28, 16, v127
	v_cndmask_b32_e64 v22, v22, v23, s[0:1]
	v_rsq_f32_e32 v30, v22
	v_lshl_add_u64 v[22:23], s[58:59], 0, v[24:25]
	v_and_b32_e32 v29, 0xffff0000, v127
	v_mov_b32_e32 v119, v97
	v_mul_f32_e32 v24, 0x45800000, v30
	v_cndmask_b32_e64 v24, v30, v24, s[0:1]
	v_pk_mul_f32 v[16:17], v[24:25], v[16:17] op_sel_hi:[0,1]
	v_pk_mul_f32 v[18:19], v[24:25], v[18:19] op_sel_hi:[0,1]
	v_lshl_add_u64 v[22:23], v[22:23], 0, s[68:69]
	v_lshl_add_u64 v[22:23], v[22:23], 0, v[118:119]
	v_pk_mul_f32 v[12:13], v[24:25], v[12:13] op_sel_hi:[0,1]
	v_pk_mul_f32 v[14:15], v[24:25], v[14:15] op_sel_hi:[0,1]
	v_pk_mul_f32 v[8:9], v[24:25], v[8:9] op_sel_hi:[0,1]
	v_pk_mul_f32 v[10:11], v[24:25], v[10:11] op_sel_hi:[0,1]
	v_pk_mul_f32 v[0:1], v[24:25], v[0:1] op_sel_hi:[0,1]
	v_pk_mul_f32 v[2:3], v[24:25], v[2:3] op_sel_hi:[0,1]
	s_add_i32 s2, s2, s86
	s_add_i32 s73, s73, s54
	s_add_i32 s55, s55, s70
	s_cmpk_gt_i32 s2, 0xfff
	s_waitcnt vmcnt(3)
	v_mov_b64_e32 v[4:5], v[198:199]
	v_mov_b64_e32 v[6:7], v[200:201]
	v_pk_mul_f32 v[4:5], v[4:5], v[16:17]
	v_pk_mul_f32 v[6:7], v[6:7], v[18:19]
	v_pk_mul_f32 v[4:5], v[4:5], v[26:27]
	v_pk_mul_f32 v[6:7], v[6:7], v[28:29]
	v_cvt_pk_bf16_f32 v4, v4, v5
	v_cvt_pk_bf16_f32 v5, v6, v7
	global_store_dwordx2 v[22:23], v[4:5], off
	v_lshlrev_b32_e32 v16, 16, v124
	v_and_b32_e32 v17, 0xffff0000, v124
	v_lshlrev_b32_e32 v18, 16, v125
	v_and_b32_e32 v19, 0xffff0000, v125
	s_waitcnt vmcnt(3)
	v_mov_b64_e32 v[4:5], v[202:203]
	v_mov_b64_e32 v[6:7], v[204:205]
	v_pk_mul_f32 v[4:5], v[4:5], v[12:13]
	v_pk_mul_f32 v[6:7], v[6:7], v[14:15]
	v_pk_mul_f32 v[4:5], v[4:5], v[16:17]
	v_pk_mul_f32 v[6:7], v[6:7], v[18:19]
	v_cvt_pk_bf16_f32 v4, v4, v5
	v_cvt_pk_bf16_f32 v5, v6, v7
	global_store_dwordx2 v[22:23], v[4:5], off offset:32
	v_lshlrev_b32_e32 v12, 16, v122
	v_and_b32_e32 v13, 0xffff0000, v122
	v_lshlrev_b32_e32 v14, 16, v123
	v_and_b32_e32 v15, 0xffff0000, v123
	s_waitcnt vmcnt(3)
	v_mov_b64_e32 v[4:5], v[208:209]
	v_mov_b64_e32 v[6:7], v[210:211]
	v_pk_mul_f32 v[4:5], v[4:5], v[8:9]
	v_pk_mul_f32 v[6:7], v[6:7], v[10:11]
	v_pk_mul_f32 v[4:5], v[4:5], v[12:13]
	v_pk_mul_f32 v[6:7], v[6:7], v[14:15]
	v_cvt_pk_bf16_f32 v4, v4, v5
	v_cvt_pk_bf16_f32 v5, v6, v7
	global_store_dwordx2 v[22:23], v[4:5], off offset:64
	v_lshlrev_b32_e32 v8, 16, v120
	v_and_b32_e32 v9, 0xffff0000, v120
	v_lshlrev_b32_e32 v10, 16, v121
	v_and_b32_e32 v11, 0xffff0000, v121
	s_waitcnt vmcnt(3)
	v_mov_b64_e32 v[4:5], v[212:213]
	v_mov_b64_e32 v[6:7], v[214:215]
	v_pk_mul_f32 v[0:1], v[4:5], v[0:1]
	v_pk_mul_f32 v[2:3], v[6:7], v[2:3]
	v_pk_mul_f32 v[0:1], v[0:1], v[8:9]
	v_pk_mul_f32 v[2:3], v[2:3], v[10:11]
	v_cvt_pk_bf16_f32 v0, v0, v1
	v_cvt_pk_bf16_f32 v1, v2, v3
	global_store_dwordx2 v[22:23], v[0:1], off offset:96
	s_barrier
	s_cbranch_scc1 .LBB0_993
